# baseline (speedup 1.0000x reference)
; template <int EPI, int AMAP, int KOFFMODE, int K>
; __device__ __forceinline__ void gemm_phase(unsigned char* smem, const bf16_t* A, int lda, const bf16_t* Bt, int NT, const EpiArgs& ea) {
;     ...
;         for (int kt = 0; kt < nk; ++kt) {
;             if (kt + 1 < nk) GEMM_DMA(m0, n0, kt + 1, cur ^ 1);
;             else if (have_next) GEMM_DMA(m0n, n0n, 0, cur ^ 1);
;             const unsigned char* Ac = smem + cur * STGB + (wm * 128 + l31) * 128;
;             const unsigned char* Bc = smem + cur * STGB + 32768 + (wn * 64 + l31) * 128;
;             bf16x8 fa[2][4], fb[2][2];
;             fb[0][0] = *(const bf16x8*)(Bc + (((0) ^ yz) & 7) * 16);
;             fb[0][1] = *(const bf16x8*)(Bc + 32 * 128 + (((0) ^ yz) & 7) * 16);
; #pragma unroll
;             for (int i = 0; i < 4; ++i) fa[0][i] = *(const bf16x8*)(Ac + i * 32 * 128 + (((0) ^ yz) & 7) * 16);
; #pragma unroll
;             for (int s = 0; s < 4; ++s) {
;                 if (s < 3) {
;                     const int o_ = (((2 * (s + 1)) ^ yz) & 7) * 16;
;                     fb[(s + 1) & 1][0] = *(const bf16x8*)(Bc + o_);
;                     fb[(s + 1) & 1][1] = *(const bf16x8*)(Bc + 32 * 128 + o_);
; #pragma unroll
;                     for (int i = 0; i < 4; ++i) fa[(s + 1) & 1][i] = *(const bf16x8*)(Ac + i * 32 * 128 + o_);
;                 }
; #pragma unroll
;                 for (int i = 0; i < 4; ++i) {
;                     acc[i][0] = __builtin_amdgcn_mfma_f32_32x32x16_bf16(fa[s & 1][i], fb[s & 1][0], acc[i][0], 0, 0, 0);
;                     acc[i][1] = __builtin_amdgcn_mfma_f32_32x32x16_bf16(fa[s & 1][i], fb[s & 1][1], acc[i][1], 0, 0, 0);
;                 }
;                 __builtin_amdgcn_sched_barrier(0);
;             }
;             if (kt + 1 < nk) asm volatile("s_waitcnt vmcnt(0)" ::: "memory");
;             __builtin_amdgcn_s_barrier();
.LBB0_461:
	s_mov_b32 s9, s13
	s_lshl_b32 s13, s9, 16
	s_xor_b32 s12, s13, 0x10000
	v_readfirstlane_b32 vcc_lo, v143
	s_nop 0
	s_add_u32 vcc_lo, vcc_lo, s12
	v_add3_u32 v155, s13, v150, v149
	v_add_u32_e32 v155, v155, v152
	v_add3_u32 v0, s13, v147, v149
	v_add_u32_e32 v0, v0, v152
	ds_read_b128 v[208:211], v155 offset:32768
	ds_read_b128 v[212:215], v155 offset:36864
	v_readfirstlane_b32 s14, v166
	s_cmp_lt_u32 s14, 0x100
	s_cbranch_scc0 .Lstg_LBB0461_0
	s_add_u32 s14, s4, 0xb240080
	s_addc_u32 s15, s5, 0
	s_mov_b32 m0, vcc_lo
	v_lshl_add_u64 v[164:165], v[136:137], 0, s[14:15]
	global_load_lds_dwordx4 v[164:165], off
	s_add_u32 s14, s4, 0xb270080
	s_addc_u32 s15, s5, 0
	s_add_u32 m0, vcc_lo, 0x2000
	v_lshl_add_u64 v[164:165], v[136:137], 0, s[14:15]
	global_load_lds_dwordx4 v[164:165], off
	s_add_u32 s14, s4, 0xb2a0080
	s_addc_u32 s15, s5, 0
	s_add_u32 m0, vcc_lo, 0x4000
	v_lshl_add_u64 v[164:165], v[136:137], 0, s[14:15]
	global_load_lds_dwordx4 v[164:165], off
	s_add_u32 s14, s4, 0xb2d0080
	s_addc_u32 s15, s5, 0
	s_add_u32 m0, vcc_lo, 0x6000
	v_lshl_add_u64 v[164:165], v[136:137], 0, s[14:15]
	global_load_lds_dwordx4 v[164:165], off
	s_add_u32 s14, s4, 0xb00080
	s_addc_u32 s15, s5, 0
	s_add_u32 m0, vcc_lo, 0x8000
	v_lshl_add_u64 v[164:165], v[138:139], 0, s[14:15]
	global_load_lds_dwordx4 v[164:165], off
	s_add_u32 s14, s4, 0xb30080
	s_addc_u32 s15, s5, 0
	s_add_u32 m0, vcc_lo, 0xa000
	v_lshl_add_u64 v[164:165], v[138:139], 0, s[14:15]
	global_load_lds_dwordx4 v[164:165], off
	s_add_u32 s14, s4, 0xb60080
	s_addc_u32 s15, s5, 0
	s_add_u32 m0, vcc_lo, 0xc000
	v_lshl_add_u64 v[164:165], v[138:139], 0, s[14:15]
	global_load_lds_dwordx4 v[164:165], off
	s_add_u32 s14, s4, 0xb90080
	s_addc_u32 s15, s5, 0
	s_add_u32 m0, vcc_lo, 0xe000
	v_lshl_add_u64 v[164:165], v[138:139], 0, s[14:15]
	global_load_lds_dwordx4 v[164:165], off
.Lstg_LBB0461_0:
	s_waitcnt lgkmcnt(5)
	v_mfma_f32_32x32x16_bf16 v[114:129], v[192:195], v[156:159], v[114:129]
	v_mfma_f32_32x32x16_bf16 v[98:113], v[192:195], v[160:163], v[98:113]
	ds_read_b128 v[192:195], v0
	s_waitcnt lgkmcnt(5)
	v_mfma_f32_32x32x16_bf16 v[82:97], v[196:199], v[156:159], v[82:97]
	v_mfma_f32_32x32x16_bf16 v[66:81], v[196:199], v[160:163], v[66:81]
	ds_read_b128 v[196:199], v0 offset:4096
	s_waitcnt lgkmcnt(5)
	v_mfma_f32_32x32x16_bf16 v[50:65], v[200:203], v[156:159], v[50:65]
	v_mfma_f32_32x32x16_bf16 v[34:49], v[200:203], v[160:163], v[34:49]
	ds_read_b128 v[200:203], v0 offset:8192
	s_waitcnt lgkmcnt(5)
	v_mfma_f32_32x32x16_bf16 v[18:33], v[204:207], v[156:159], v[18:33]
	v_mfma_f32_32x32x16_bf16 v[2:17], v[204:207], v[160:163], v[2:17]
	ds_read_b128 v[204:207], v0 offset:12288
	v_add3_u32 v155, s13, v150, v149
	v_add_u32_e32 v155, v155, v153
	v_add3_u32 v0, s13, v147, v149
	v_add_u32_e32 v0, v0, v153
	ds_read_b128 v[156:159], v155 offset:32768
	ds_read_b128 v[160:163], v155 offset:36864
	v_readfirstlane_b32 s14, v166
	s_cmp_lt_u32 s14, 0x100
	s_cbranch_scc1 .Lstg_LBB0461_1
	s_add_u32 s14, s4, 0xb240080
	s_addc_u32 s15, s5, 0
	s_mov_b32 m0, vcc_lo
	v_lshl_add_u64 v[164:165], v[136:137], 0, s[14:15]
	global_load_lds_dwordx4 v[164:165], off
	s_add_u32 s14, s4, 0xb270080
	s_addc_u32 s15, s5, 0
	s_add_u32 m0, vcc_lo, 0x2000
	v_lshl_add_u64 v[164:165], v[136:137], 0, s[14:15]
	global_load_lds_dwordx4 v[164:165], off
	s_add_u32 s14, s4, 0xb2a0080
	s_addc_u32 s15, s5, 0
	s_add_u32 m0, vcc_lo, 0x4000
	v_lshl_add_u64 v[164:165], v[136:137], 0, s[14:15]
	global_load_lds_dwordx4 v[164:165], off
	s_add_u32 s14, s4, 0xb2d0080
	s_addc_u32 s15, s5, 0
	s_add_u32 m0, vcc_lo, 0x6000
	v_lshl_add_u64 v[164:165], v[136:137], 0, s[14:15]
	global_load_lds_dwordx4 v[164:165], off
	s_add_u32 s14, s4, 0xb00080
	s_addc_u32 s15, s5, 0
	s_add_u32 m0, vcc_lo, 0x8000
	v_lshl_add_u64 v[164:165], v[138:139], 0, s[14:15]
	global_load_lds_dwordx4 v[164:165], off
	s_add_u32 s14, s4, 0xb30080
	s_addc_u32 s15, s5, 0
	s_add_u32 m0, vcc_lo, 0xa000
	v_lshl_add_u64 v[164:165], v[138:139], 0, s[14:15]
	global_load_lds_dwordx4 v[164:165], off
	s_add_u32 s14, s4, 0xb60080
	s_addc_u32 s15, s5, 0
	s_add_u32 m0, vcc_lo, 0xc000
	v_lshl_add_u64 v[164:165], v[138:139], 0, s[14:15]
	global_load_lds_dwordx4 v[164:165], off
	s_add_u32 s14, s4, 0xb90080
	s_addc_u32 s15, s5, 0
	s_add_u32 m0, vcc_lo, 0xe000
	v_lshl_add_u64 v[164:165], v[138:139], 0, s[14:15]
	global_load_lds_dwordx4 v[164:165], off
; template <int EPI, int AMAP, int KOFFMODE, int K>
; __device__ __forceinline__ void gemm_phase(unsigned char* smem, const bf16_t* A, int lda, const bf16_t* Bt, int NT, const EpiArgs& ea) {
;     ...
;             for (int s = 0; s < 4; ++s) {
;                 if (s < 3) {
;                     const int o_ = (((2 * (s + 1)) ^ yz) & 7) * 16;
;                     fb[(s + 1) & 1][0] = *(const bf16x8*)(Bc + o_);
;                     fb[(s + 1) & 1][1] = *(const bf16x8*)(Bc + 32 * 128 + o_);
; #pragma unroll
;                     for (int i = 0; i < 4; ++i) fa[(s + 1) & 1][i] = *(const bf16x8*)(Ac + i * 32 * 128 + o_);
;                 }
; #pragma unroll
;                 for (int i = 0; i < 4; ++i) {
;                     acc[i][0] = __builtin_amdgcn_mfma_f32_32x32x16_bf16(fa[s & 1][i], fb[s & 1][0], acc[i][0], 0, 0, 0);
;                     acc[i][1] = __builtin_amdgcn_mfma_f32_32x32x16_bf16(fa[s & 1][i], fb[s & 1][1], acc[i][1], 0, 0, 0);
;                 }
;                 __builtin_amdgcn_sched_barrier(0);
;             }
;             if (kt + 1 < nk) asm volatile("s_waitcnt vmcnt(0)" ::: "memory");
;             __builtin_amdgcn_s_barrier();
;             cur ^= 1;
;         }
.Lstg_LBB0461_1:
	s_waitcnt lgkmcnt(5)
	v_mfma_f32_32x32x16_bf16 v[114:129], v[192:195], v[208:211], v[114:129]
	v_mfma_f32_32x32x16_bf16 v[98:113], v[192:195], v[212:215], v[98:113]
	ds_read_b128 v[192:195], v0
	s_waitcnt lgkmcnt(5)
	v_mfma_f32_32x32x16_bf16 v[82:97], v[196:199], v[208:211], v[82:97]
	v_mfma_f32_32x32x16_bf16 v[66:81], v[196:199], v[212:215], v[66:81]
	ds_read_b128 v[196:199], v0 offset:4096
	s_waitcnt lgkmcnt(5)
	v_mfma_f32_32x32x16_bf16 v[50:65], v[200:203], v[208:211], v[50:65]
	v_mfma_f32_32x32x16_bf16 v[34:49], v[200:203], v[212:215], v[34:49]
	ds_read_b128 v[200:203], v0 offset:8192
	s_waitcnt lgkmcnt(5)
	v_mfma_f32_32x32x16_bf16 v[18:33], v[204:207], v[208:211], v[18:33]
	v_mfma_f32_32x32x16_bf16 v[2:17], v[204:207], v[212:215], v[2:17]
	ds_read_b128 v[204:207], v0 offset:12288
	v_add3_u32 v155, s13, v150, v149
	v_add_u32_e32 v155, v155, v154
	v_add3_u32 v0, s13, v147, v149
	v_add_u32_e32 v0, v0, v154
	ds_read_b128 v[208:211], v155 offset:32768
	ds_read_b128 v[212:215], v155 offset:36864
	s_waitcnt lgkmcnt(5)
	v_mfma_f32_32x32x16_bf16 v[114:129], v[192:195], v[156:159], v[114:129]
	v_mfma_f32_32x32x16_bf16 v[98:113], v[192:195], v[160:163], v[98:113]
	ds_read_b128 v[192:195], v0
	s_waitcnt lgkmcnt(5)
	v_mfma_f32_32x32x16_bf16 v[82:97], v[196:199], v[156:159], v[82:97]
	v_mfma_f32_32x32x16_bf16 v[66:81], v[196:199], v[160:163], v[66:81]
	ds_read_b128 v[196:199], v0 offset:4096
	s_waitcnt lgkmcnt(5)
	v_mfma_f32_32x32x16_bf16 v[50:65], v[200:203], v[156:159], v[50:65]
	v_mfma_f32_32x32x16_bf16 v[34:49], v[200:203], v[160:163], v[34:49]
	ds_read_b128 v[200:203], v0 offset:8192
	s_waitcnt lgkmcnt(5)
	v_mfma_f32_32x32x16_bf16 v[18:33], v[204:207], v[156:159], v[18:33]
	v_mfma_f32_32x32x16_bf16 v[2:17], v[204:207], v[160:163], v[2:17]
	ds_read_b128 v[204:207], v0 offset:12288
	s_waitcnt lgkmcnt(3)
	v_mfma_f32_32x32x16_bf16 v[114:129], v[192:195], v[208:211], v[114:129]
	v_mfma_f32_32x32x16_bf16 v[98:113], v[192:195], v[212:215], v[98:113]
	s_waitcnt lgkmcnt(2)
	v_mfma_f32_32x32x16_bf16 v[82:97], v[196:199], v[208:211], v[82:97]
	v_mfma_f32_32x32x16_bf16 v[66:81], v[196:199], v[212:215], v[66:81]
	s_waitcnt lgkmcnt(0)
	s_waitcnt vmcnt(0)
	s_barrier
	v_add3_u32 v155, s12, v150, v149
	v_add_u32_e32 v155, v155, v151
	v_add3_u32 v0, s12, v147, v149
	v_add_u32_e32 v0, v0, v151
	ds_read_b128 v[156:159], v155 offset:32768
	ds_read_b128 v[160:163], v155 offset:36864
	ds_read_b128 v[192:195], v0
	ds_read_b128 v[196:199], v0 offset:4096
	v_mfma_f32_32x32x16_bf16 v[50:65], v[200:203], v[208:211], v[50:65]
	v_mfma_f32_32x32x16_bf16 v[34:49], v[200:203], v[212:215], v[34:49]
	ds_read_b128 v[200:203], v0 offset:8192
	v_mfma_f32_32x32x16_bf16 v[18:33], v[204:207], v[208:211], v[18:33]
	v_mfma_f32_32x32x16_bf16 v[2:17], v[204:207], v[212:215], v[2:17]
	ds_read_b128 v[204:207], v0 offset:12288
	s_xor_b32 s13, s9, 1
	s_add_u32 s4, s4, 0x80
	s_addc_u32 s5, s5, 0
	s_cmpk_eq_i32 s4, 0xb80
	s_cbranch_scc0 .LBB0_461
	s_waitcnt lgkmcnt(0)
	s_andn2_b64 vcc, exec, s[2:3]
	s_lshl_b32 s2, s13, 16
	s_cbranch_vccnz .LBB0_453
	v_add_u32_e32 v0, s8, v142
	s_xor_b32 s3, s2, 0x10000
	v_mad_i64_i32 v[138:139], s[4:5], v0, s37, v[130:131]
	v_add_u32_e32 v0, s3, v143
	v_add_u32_e32 v136, s7, v142
	v_add_u32_e32 v155, 0x8000, v0
	v_readfirstlane_b32 s3, v0
	v_mad_i64_i32 v[136:137], s[4:5], v136, s37, v[132:133]
	s_mov_b32 m0, s3
	v_readfirstlane_b32 s3, v155
	v_add_u32_e32 v155, 0x2000, v0
	global_load_lds_dwordx4 v[138:139], off
	s_mov_b32 m0, s3
	s_mov_b64 s[4:5], 0x30000
	v_readfirstlane_b32 s3, v155
	v_add_u32_e32 v155, 0xa000, v0
	global_load_lds_dwordx4 v[136:137], off
	v_lshl_add_u64 v[156:157], v[138:139], 0, s[4:5]
	s_mov_b32 m0, s3
	v_readfirstlane_b32 s3, v155
	v_add_u32_e32 v155, 0x4000, v0
	global_load_lds_dwordx4 v[156:157], off
	v_lshl_add_u64 v[156:157], v[136:137], 0, s[4:5]
	s_mov_b32 m0, s3
	s_mov_b64 s[4:5], 0x60000
	v_readfirstlane_b32 s3, v155
	v_add_u32_e32 v155, 0xc000, v0
	global_load_lds_dwordx4 v[156:157], off
	v_lshl_add_u64 v[156:157], v[138:139], 0, s[4:5]
	s_mov_b32 m0, s3
	v_readfirstlane_b32 s3, v155
	v_add_u32_e32 v155, 0x6000, v0
	global_load_lds_dwordx4 v[156:157], off
	v_lshl_add_u64 v[156:157], v[136:137], 0, s[4:5]
	s_mov_b32 m0, s3
	s_mov_b64 s[4:5], 0x90000
	v_readfirstlane_b32 s3, v155
	v_add_u32_e32 v0, 0xe000, v0
	global_load_lds_dwordx4 v[156:157], off
	v_lshl_add_u64 v[138:139], v[138:139], 0, s[4:5]
	s_mov_b32 m0, s3
	v_readfirstlane_b32 s3, v0
	global_load_lds_dwordx4 v[138:139], off
	v_lshl_add_u64 v[136:137], v[136:137], 0, s[4:5]
	s_mov_b32 m0, s3
	s_nop 0
	global_load_lds_dwordx4 v[136:137], off
	s_branch .LBB0_453

; template <int EPI, int AMAP, int KOFFMODE, int K>
; __device__ __forceinline__ void gemm_phase(unsigned char* smem, const bf16_t* A, int lda, const bf16_t* Bt, int NT, const EpiArgs& ea) {
;     ...
;         for (int kt = 0; kt < nk; ++kt) {
;             if (kt + 1 < nk) GEMM_DMA(m0, n0, kt + 1, cur ^ 1);
;             else if (have_next) GEMM_DMA(m0n, n0n, 0, cur ^ 1);
;             const unsigned char* Ac = smem + cur * STGB + (wm * 128 + l31) * 128;
;             const unsigned char* Bc = smem + cur * STGB + 32768 + (wn * 64 + l31) * 128;
;             bf16x8 fa[2][4], fb[2][2];
;             fb[0][0] = *(const bf16x8*)(Bc + (((0) ^ yz) & 7) * 16);
;             fb[0][1] = *(const bf16x8*)(Bc + 32 * 128 + (((0) ^ yz) & 7) * 16);
; #pragma unroll
;             for (int i = 0; i < 4; ++i) fa[0][i] = *(const bf16x8*)(Ac + i * 32 * 128 + (((0) ^ yz) & 7) * 16);
; #pragma unroll
;             for (int s = 0; s < 4; ++s) {
;                 if (s < 3) {
;                     const int o_ = (((2 * (s + 1)) ^ yz) & 7) * 16;
;                     fb[(s + 1) & 1][0] = *(const bf16x8*)(Bc + o_);
;                     fb[(s + 1) & 1][1] = *(const bf16x8*)(Bc + 32 * 128 + o_);
; #pragma unroll
;                     for (int i = 0; i < 4; ++i) fa[(s + 1) & 1][i] = *(const bf16x8*)(Ac + i * 32 * 128 + o_);
;                 }
; #pragma unroll
;                 for (int i = 0; i < 4; ++i) {
;                     acc[i][0] = __builtin_amdgcn_mfma_f32_32x32x16_bf16(fa[s & 1][i], fb[s & 1][0], acc[i][0], 0, 0, 0);
;                     acc[i][1] = __builtin_amdgcn_mfma_f32_32x32x16_bf16(fa[s & 1][i], fb[s & 1][1], acc[i][1], 0, 0, 0);
;                 }
;                 __builtin_amdgcn_sched_barrier(0);
;             }
;             if (kt + 1 < nk) asm volatile("s_waitcnt vmcnt(0)" ::: "memory");
;             __builtin_amdgcn_s_barrier();
.LBB0_927:
	s_lshr_b32 s14, s12, 1
	s_mulk_i32 s14, 0xc0
	s_and_b32 s20, s13, 64
	s_add_i32 s20, s14, s20
	s_mov_b32 s9, s15
	s_lshl_b32 s15, s9, 16
	s_xor_b32 s14, s15, 0x10000
	v_readfirstlane_b32 s28, v143
	s_nop 0
	s_add_u32 s28, s28, s14
	v_add3_u32 v155, s15, v150, v149
	v_add_u32_e32 v155, v155, v152
	v_add3_u32 v0, s15, v147, v149
	v_add_u32_e32 v0, v0, v152
	ds_read_b128 v[208:211], v155 offset:32768
	ds_read_b128 v[212:215], v155 offset:36864
	v_readfirstlane_b32 s34, v166
	s_cmp_lt_u32 s34, 0x100
	s_cbranch_scc0 .Lstg_LBB0927_0
	s_lshl_b64 s[34:35], s[20:21], 1
	s_mov_b32 m0, s28
	v_lshl_add_u64 v[164:165], v[136:137], 0, s[34:35]
	global_load_lds_dwordx4 v[164:165], off
	s_lshl_b64 s[34:35], s[20:21], 1
	s_add_u32 s34, s34, 0x60000
	s_addc_u32 s35, s35, 0
	s_add_u32 m0, s28, 0x2000
	v_lshl_add_u64 v[164:165], v[136:137], 0, s[34:35]
	global_load_lds_dwordx4 v[164:165], off
	s_lshl_b64 s[34:35], s[20:21], 1
	s_add_u32 s34, s34, 0xc0000
	s_addc_u32 s35, s35, 0
	s_add_u32 m0, s28, 0x4000
	v_lshl_add_u64 v[164:165], v[136:137], 0, s[34:35]
	global_load_lds_dwordx4 v[164:165], off
	s_lshl_b64 s[34:35], s[20:21], 1
	s_add_u32 s34, s34, 0x120000
	s_addc_u32 s35, s35, 0
	s_add_u32 m0, s28, 0x6000
	v_lshl_add_u64 v[164:165], v[136:137], 0, s[34:35]
	global_load_lds_dwordx4 v[164:165], off
	s_add_u32 s34, s4, 0x7c0080
	s_addc_u32 s35, s5, 0
	s_add_u32 m0, s28, 0x8000
	v_lshl_add_u64 v[164:165], v[138:139], 0, s[34:35]
	global_load_lds_dwordx4 v[164:165], off
	s_add_u32 s34, s4, s68
	s_addc_u32 s35, s5, s69
	s_add_u32 m0, s28, 0xa000
	v_lshl_add_u64 v[164:165], v[138:139], 0, s[34:35]
	global_load_lds_dwordx4 v[164:165], off
	s_add_u32 s34, s4, s80
	s_addc_u32 s35, s5, s81
	s_add_u32 m0, s28, 0xc000
	v_lshl_add_u64 v[164:165], v[138:139], 0, s[34:35]
	global_load_lds_dwordx4 v[164:165], off
	s_add_u32 s34, s4, 0x880080
	s_addc_u32 s35, s5, 0
	s_add_u32 m0, s28, 0xe000
	v_lshl_add_u64 v[164:165], v[138:139], 0, s[34:35]
	global_load_lds_dwordx4 v[164:165], off
.Lstg_LBB0927_0:
	s_waitcnt lgkmcnt(5)
	v_mfma_f32_32x32x16_bf16 v[114:129], v[192:195], v[156:159], v[114:129]
	v_mfma_f32_32x32x16_bf16 v[98:113], v[192:195], v[160:163], v[98:113]
	ds_read_b128 v[192:195], v0
	s_waitcnt lgkmcnt(5)
	v_mfma_f32_32x32x16_bf16 v[82:97], v[196:199], v[156:159], v[82:97]
	v_mfma_f32_32x32x16_bf16 v[66:81], v[196:199], v[160:163], v[66:81]
	ds_read_b128 v[196:199], v0 offset:4096
	s_waitcnt lgkmcnt(5)
	v_mfma_f32_32x32x16_bf16 v[50:65], v[200:203], v[156:159], v[50:65]
	v_mfma_f32_32x32x16_bf16 v[34:49], v[200:203], v[160:163], v[34:49]
	ds_read_b128 v[200:203], v0 offset:8192
	s_waitcnt lgkmcnt(5)
	v_mfma_f32_32x32x16_bf16 v[18:33], v[204:207], v[156:159], v[18:33]
	v_mfma_f32_32x32x16_bf16 v[2:17], v[204:207], v[160:163], v[2:17]
	ds_read_b128 v[204:207], v0 offset:12288
	v_add3_u32 v155, s15, v150, v149
	v_add_u32_e32 v155, v155, v153
	v_add3_u32 v0, s15, v147, v149
	v_add_u32_e32 v0, v0, v153
	ds_read_b128 v[156:159], v155 offset:32768
	ds_read_b128 v[160:163], v155 offset:36864
	v_readfirstlane_b32 s34, v166
	s_cmp_lt_u32 s34, 0x100
	s_cbranch_scc1 .Lstg_LBB0927_1
	s_lshl_b64 s[34:35], s[20:21], 1
	s_mov_b32 m0, s28
	v_lshl_add_u64 v[164:165], v[136:137], 0, s[34:35]
	global_load_lds_dwordx4 v[164:165], off
	s_lshl_b64 s[34:35], s[20:21], 1
	s_add_u32 s34, s34, 0x60000
	s_addc_u32 s35, s35, 0
	s_add_u32 m0, s28, 0x2000
	v_lshl_add_u64 v[164:165], v[136:137], 0, s[34:35]
	global_load_lds_dwordx4 v[164:165], off
	s_lshl_b64 s[34:35], s[20:21], 1
	s_add_u32 s34, s34, 0xc0000
	s_addc_u32 s35, s35, 0
	s_add_u32 m0, s28, 0x4000
	v_lshl_add_u64 v[164:165], v[136:137], 0, s[34:35]
	global_load_lds_dwordx4 v[164:165], off
	s_lshl_b64 s[34:35], s[20:21], 1
	s_add_u32 s34, s34, 0x120000
	s_addc_u32 s35, s35, 0
	s_add_u32 m0, s28, 0x6000
	v_lshl_add_u64 v[164:165], v[136:137], 0, s[34:35]
	global_load_lds_dwordx4 v[164:165], off
	s_add_u32 s34, s4, 0x7c0080
	s_addc_u32 s35, s5, 0
	s_add_u32 m0, s28, 0x8000
	v_lshl_add_u64 v[164:165], v[138:139], 0, s[34:35]
	global_load_lds_dwordx4 v[164:165], off
	s_add_u32 s34, s4, s68
	s_addc_u32 s35, s5, s69
	s_add_u32 m0, s28, 0xa000
	v_lshl_add_u64 v[164:165], v[138:139], 0, s[34:35]
	global_load_lds_dwordx4 v[164:165], off
	s_add_u32 s34, s4, s80
	s_addc_u32 s35, s5, s81
	s_add_u32 m0, s28, 0xc000
	v_lshl_add_u64 v[164:165], v[138:139], 0, s[34:35]
	global_load_lds_dwordx4 v[164:165], off
	s_add_u32 s34, s4, 0x880080
	s_addc_u32 s35, s5, 0
	s_add_u32 m0, s28, 0xe000
	v_lshl_add_u64 v[164:165], v[138:139], 0, s[34:35]
	global_load_lds_dwordx4 v[164:165], off
; template <int EPI, int AMAP, int KOFFMODE, int K>
; __device__ __forceinline__ void gemm_phase(unsigned char* smem, const bf16_t* A, int lda, const bf16_t* Bt, int NT, const EpiArgs& ea) {
;     ...
;             for (int s = 0; s < 4; ++s) {
;                 if (s < 3) {
;                     const int o_ = (((2 * (s + 1)) ^ yz) & 7) * 16;
;                     fb[(s + 1) & 1][0] = *(const bf16x8*)(Bc + o_);
;                     fb[(s + 1) & 1][1] = *(const bf16x8*)(Bc + 32 * 128 + o_);
; #pragma unroll
;                     for (int i = 0; i < 4; ++i) fa[(s + 1) & 1][i] = *(const bf16x8*)(Ac + i * 32 * 128 + o_);
;                 }
; #pragma unroll
;                 for (int i = 0; i < 4; ++i) {
;                     acc[i][0] = __builtin_amdgcn_mfma_f32_32x32x16_bf16(fa[s & 1][i], fb[s & 1][0], acc[i][0], 0, 0, 0);
;                     acc[i][1] = __builtin_amdgcn_mfma_f32_32x32x16_bf16(fa[s & 1][i], fb[s & 1][1], acc[i][1], 0, 0, 0);
;                 }
;                 __builtin_amdgcn_sched_barrier(0);
;             }
;             if (kt + 1 < nk) asm volatile("s_waitcnt vmcnt(0)" ::: "memory");
;             __builtin_amdgcn_s_barrier();
;             cur ^= 1;
;         }
.Lstg_LBB0927_1:
	s_waitcnt lgkmcnt(5)
	v_mfma_f32_32x32x16_bf16 v[114:129], v[192:195], v[208:211], v[114:129]
	v_mfma_f32_32x32x16_bf16 v[98:113], v[192:195], v[212:215], v[98:113]
	ds_read_b128 v[192:195], v0
	s_waitcnt lgkmcnt(5)
	v_mfma_f32_32x32x16_bf16 v[82:97], v[196:199], v[208:211], v[82:97]
	v_mfma_f32_32x32x16_bf16 v[66:81], v[196:199], v[212:215], v[66:81]
	ds_read_b128 v[196:199], v0 offset:4096
	s_waitcnt lgkmcnt(5)
	v_mfma_f32_32x32x16_bf16 v[50:65], v[200:203], v[208:211], v[50:65]
	v_mfma_f32_32x32x16_bf16 v[34:49], v[200:203], v[212:215], v[34:49]
	ds_read_b128 v[200:203], v0 offset:8192
	s_waitcnt lgkmcnt(5)
	v_mfma_f32_32x32x16_bf16 v[18:33], v[204:207], v[208:211], v[18:33]
	v_mfma_f32_32x32x16_bf16 v[2:17], v[204:207], v[212:215], v[2:17]
	ds_read_b128 v[204:207], v0 offset:12288
	v_add3_u32 v155, s15, v150, v149
	v_add_u32_e32 v155, v155, v154
	v_add3_u32 v0, s15, v147, v149
	v_add_u32_e32 v0, v0, v154
	ds_read_b128 v[208:211], v155 offset:32768
	ds_read_b128 v[212:215], v155 offset:36864
	s_waitcnt lgkmcnt(5)
	v_mfma_f32_32x32x16_bf16 v[114:129], v[192:195], v[156:159], v[114:129]
	v_mfma_f32_32x32x16_bf16 v[98:113], v[192:195], v[160:163], v[98:113]
	ds_read_b128 v[192:195], v0
	s_waitcnt lgkmcnt(5)
	v_mfma_f32_32x32x16_bf16 v[82:97], v[196:199], v[156:159], v[82:97]
	v_mfma_f32_32x32x16_bf16 v[66:81], v[196:199], v[160:163], v[66:81]
	ds_read_b128 v[196:199], v0 offset:4096
	s_waitcnt lgkmcnt(5)
	v_mfma_f32_32x32x16_bf16 v[50:65], v[200:203], v[156:159], v[50:65]
	v_mfma_f32_32x32x16_bf16 v[34:49], v[200:203], v[160:163], v[34:49]
	ds_read_b128 v[200:203], v0 offset:8192
	s_waitcnt lgkmcnt(5)
	v_mfma_f32_32x32x16_bf16 v[18:33], v[204:207], v[156:159], v[18:33]
	v_mfma_f32_32x32x16_bf16 v[2:17], v[204:207], v[160:163], v[2:17]
	ds_read_b128 v[204:207], v0 offset:12288
	s_waitcnt lgkmcnt(3)
	v_mfma_f32_32x32x16_bf16 v[114:129], v[192:195], v[208:211], v[114:129]
	v_mfma_f32_32x32x16_bf16 v[98:113], v[192:195], v[212:215], v[98:113]
	s_waitcnt lgkmcnt(2)
	v_mfma_f32_32x32x16_bf16 v[82:97], v[196:199], v[208:211], v[82:97]
	v_mfma_f32_32x32x16_bf16 v[66:81], v[196:199], v[212:215], v[66:81]
	s_waitcnt lgkmcnt(0)
	s_waitcnt vmcnt(0)
	s_barrier
	v_add3_u32 v155, s14, v150, v149
	v_add_u32_e32 v155, v155, v151
	v_add3_u32 v0, s14, v147, v149
	v_add_u32_e32 v0, v0, v151
	ds_read_b128 v[156:159], v155 offset:32768
	ds_read_b128 v[160:163], v155 offset:36864
	ds_read_b128 v[192:195], v0
	ds_read_b128 v[196:199], v0 offset:4096
	v_mfma_f32_32x32x16_bf16 v[50:65], v[200:203], v[208:211], v[50:65]
	v_mfma_f32_32x32x16_bf16 v[34:49], v[200:203], v[212:215], v[34:49]
	ds_read_b128 v[200:203], v0 offset:8192
	v_mfma_f32_32x32x16_bf16 v[18:33], v[204:207], v[208:211], v[18:33]
	v_mfma_f32_32x32x16_bf16 v[2:17], v[204:207], v[212:215], v[2:17]
	ds_read_b128 v[204:207], v0 offset:12288
	s_xor_b32 s15, s9, 1
	s_add_u32 s4, s4, 0x80
	s_addc_u32 s5, s5, 0
	s_add_i32 s12, s12, 1
	s_add_i32 s13, s13, 64
	s_mov_b64 s[34:35], 0x60000
	s_cmpk_eq_i32 s4, 0xf80
	s_cbranch_scc0 .LBB0_927
	s_waitcnt lgkmcnt(0)
	v_writelane_b32 v251, s20, 18
	s_andn2_b64 vcc, exec, s[2:3]
	s_lshl_b32 s2, s15, 16
	v_writelane_b32 v251, s21, 19
	s_cbranch_vccnz .LBB0_919
	v_add_u32_e32 v0, s8, v142
	s_movk_i32 s3, 0x1800
	v_mad_i64_i32 v[138:139], s[4:5], v0, s3, v[130:131]
	s_xor_b32 s3, s2, 0x10000
	v_add_u32_e32 v136, s7, v142
	v_add_u32_e32 v0, s3, v143
	v_ashrrev_i32_e32 v137, 31, v136
	v_add_u32_e32 v155, 0x8000, v0
	v_readfirstlane_b32 s3, v0
	v_lshlrev_b64 v[136:137], 12, v[136:137]
	s_mov_b32 m0, s3
	v_readfirstlane_b32 s3, v155
	v_add_u32_e32 v155, 0x2000, v0
	v_lshl_add_u64 v[136:137], v[132:133], 0, v[136:137]
	global_load_lds_dwordx4 v[138:139], off
	s_mov_b32 m0, s3
	v_readfirstlane_b32 s3, v155
	v_add_u32_e32 v155, 0xa000, v0
	global_load_lds_dwordx4 v[136:137], off
	v_lshl_add_u64 v[156:157], v[138:139], 0, s[34:35]
	s_mov_b32 m0, s3
	s_mov_b64 s[4:5], 0x40000
	v_readfirstlane_b32 s3, v155
	v_add_u32_e32 v155, 0x4000, v0
	global_load_lds_dwordx4 v[156:157], off
	v_lshl_add_u64 v[156:157], v[136:137], 0, s[4:5]
	s_mov_b32 m0, s3
	s_mov_b64 s[4:5], 0xc0000
	v_readfirstlane_b32 s3, v155
	v_add_u32_e32 v155, 0xc000, v0
	global_load_lds_dwordx4 v[156:157], off
	v_lshl_add_u64 v[156:157], v[138:139], 0, s[4:5]
	s_mov_b32 m0, s3
	s_mov_b64 s[12:13], 0x80000
	v_readfirstlane_b32 s3, v155
	v_add_u32_e32 v155, 0x6000, v0
	global_load_lds_dwordx4 v[156:157], off
	v_lshl_add_u64 v[156:157], v[136:137], 0, s[12:13]
	s_mov_b32 m0, s3
	s_mov_b64 s[12:13], 0x120000
	v_readfirstlane_b32 s3, v155
	v_add_u32_e32 v0, 0xe000, v0
	global_load_lds_dwordx4 v[156:157], off
	v_lshl_add_u64 v[138:139], v[138:139], 0, s[12:13]
	s_mov_b32 m0, s3
	v_readfirstlane_b32 s3, v0
	global_load_lds_dwordx4 v[138:139], off
	v_lshl_add_u64 v[136:137], v[136:137], 0, s[4:5]
	s_mov_b32 m0, s3
	s_nop 0
	global_load_lds_dwordx4 v[136:137], off
	s_branch .LBB0_919

; template <int EPI, int AMAP, int KOFFMODE, int K>
; __device__ __forceinline__ void gemm_phase(unsigned char* smem, const bf16_t* A, int lda, const bf16_t* Bt, int NT, const EpiArgs& ea) {
;     ...
;         for (int kt = 0; kt < nk; ++kt) {
;             if (kt + 1 < nk) GEMM_DMA(m0, n0, kt + 1, cur ^ 1);
;             else if (have_next) GEMM_DMA(m0n, n0n, 0, cur ^ 1);
;             const unsigned char* Ac = smem + cur * STGB + (wm * 128 + l31) * 128;
;             const unsigned char* Bc = smem + cur * STGB + 32768 + (wn * 64 + l31) * 128;
;             bf16x8 fa[2][4], fb[2][2];
;             fb[0][0] = *(const bf16x8*)(Bc + (((0) ^ yz) & 7) * 16);
;             fb[0][1] = *(const bf16x8*)(Bc + 32 * 128 + (((0) ^ yz) & 7) * 16);
; #pragma unroll
;             for (int i = 0; i < 4; ++i) fa[0][i] = *(const bf16x8*)(Ac + i * 32 * 128 + (((0) ^ yz) & 7) * 16);
; #pragma unroll
;             for (int s = 0; s < 4; ++s) {
;                 if (s < 3) {
;                     const int o_ = (((2 * (s + 1)) ^ yz) & 7) * 16;
;                     fb[(s + 1) & 1][0] = *(const bf16x8*)(Bc + o_);
;                     fb[(s + 1) & 1][1] = *(const bf16x8*)(Bc + 32 * 128 + o_);
; #pragma unroll
;                     for (int i = 0; i < 4; ++i) fa[(s + 1) & 1][i] = *(const bf16x8*)(Ac + i * 32 * 128 + o_);
;                 }
; #pragma unroll
;                 for (int i = 0; i < 4; ++i) {
;                     acc[i][0] = __builtin_amdgcn_mfma_f32_32x32x16_bf16(fa[s & 1][i], fb[s & 1][0], acc[i][0], 0, 0, 0);
;                     acc[i][1] = __builtin_amdgcn_mfma_f32_32x32x16_bf16(fa[s & 1][i], fb[s & 1][1], acc[i][1], 0, 0, 0);
;                 }
;                 __builtin_amdgcn_sched_barrier(0);
;             }
;             if (kt + 1 < nk) asm volatile("s_waitcnt vmcnt(0)" ::: "memory");
;             __builtin_amdgcn_s_barrier();
.LBB0_1032:
	s_mov_b32 s11, s15
	s_lshl_b32 s15, s11, 16
	s_xor_b32 s14, s15, 0x10000
	v_readfirstlane_b32 s28, v144
	s_nop 0
	s_add_u32 s28, s28, s14
	v_add3_u32 v191, s15, v151, v150
	v_add_u32_e32 v191, v191, v153
	v_add3_u32 v0, s15, v149, v150
	v_add_u32_e32 v0, v0, v153
	ds_read_b128 v[208:211], v191 offset:32768
	ds_read_b128 v[212:215], v191 offset:36864
	v_readfirstlane_b32 s34, v166
	s_cmp_lt_u32 s34, 0x100
	s_cbranch_scc0 .Lstg_LBB01032_0
	s_add_u32 s34, s4, s20
	s_addc_u32 s35, s5, s21
	s_mov_b32 m0, s28
	v_lshl_add_u64 v[164:165], v[136:137], 0, s[34:35]
	global_load_lds_dwordx4 v[164:165], off
	s_add_u32 s34, s4, vcc_lo
	s_addc_u32 s35, s5, vcc_hi
	s_add_u32 m0, s28, 0x2000
	v_lshl_add_u64 v[164:165], v[136:137], 0, s[34:35]
	global_load_lds_dwordx4 v[164:165], off
	s_add_u32 s34, s4, s68
	s_addc_u32 s35, s5, s69
	s_add_u32 m0, s28, 0x4000
	v_lshl_add_u64 v[164:165], v[136:137], 0, s[34:35]
	global_load_lds_dwordx4 v[164:165], off
	s_add_u32 s34, s4, s88
	s_addc_u32 s35, s5, s89
	s_add_u32 m0, s28, 0x6000
	v_lshl_add_u64 v[164:165], v[136:137], 0, s[34:35]
	global_load_lds_dwordx4 v[164:165], off
	s_add_u32 s34, s4, 0xe00080
	s_addc_u32 s35, s5, 0
	s_add_u32 m0, s28, 0x8000
	v_lshl_add_u64 v[164:165], v[138:139], 0, s[34:35]
	global_load_lds_dwordx4 v[164:165], off
	s_add_u32 s34, s4, 0xe20080
	s_addc_u32 s35, s5, 0
	s_add_u32 m0, s28, 0xa000
	v_lshl_add_u64 v[164:165], v[138:139], 0, s[34:35]
	global_load_lds_dwordx4 v[164:165], off
	s_add_u32 s34, s4, 0xe40080
	s_addc_u32 s35, s5, 0
	s_add_u32 m0, s28, 0xc000
	v_lshl_add_u64 v[164:165], v[138:139], 0, s[34:35]
	global_load_lds_dwordx4 v[164:165], off
	s_add_u32 s34, s4, 0xe60080
	s_addc_u32 s35, s5, 0
	s_add_u32 m0, s28, 0xe000
	v_lshl_add_u64 v[164:165], v[138:139], 0, s[34:35]
	global_load_lds_dwordx4 v[164:165], off
.Lstg_LBB01032_0:
	s_waitcnt lgkmcnt(5)
	v_mfma_f32_32x32x16_bf16 v[114:129], v[192:195], v[156:159], v[114:129]
	v_mfma_f32_32x32x16_bf16 v[98:113], v[192:195], v[160:163], v[98:113]
	ds_read_b128 v[192:195], v0
	s_waitcnt lgkmcnt(5)
	v_mfma_f32_32x32x16_bf16 v[82:97], v[196:199], v[156:159], v[82:97]
	v_mfma_f32_32x32x16_bf16 v[66:81], v[196:199], v[160:163], v[66:81]
	ds_read_b128 v[196:199], v0 offset:4096
	s_waitcnt lgkmcnt(5)
	v_mfma_f32_32x32x16_bf16 v[50:65], v[200:203], v[156:159], v[50:65]
	v_mfma_f32_32x32x16_bf16 v[34:49], v[200:203], v[160:163], v[34:49]
	ds_read_b128 v[200:203], v0 offset:8192
	s_waitcnt lgkmcnt(5)
	v_mfma_f32_32x32x16_bf16 v[18:33], v[204:207], v[156:159], v[18:33]
	v_mfma_f32_32x32x16_bf16 v[2:17], v[204:207], v[160:163], v[2:17]
	ds_read_b128 v[204:207], v0 offset:12288
	v_add3_u32 v191, s15, v151, v150
	v_add_u32_e32 v191, v191, v154
	v_add3_u32 v0, s15, v149, v150
	v_add_u32_e32 v0, v0, v154
	ds_read_b128 v[156:159], v191 offset:32768
	ds_read_b128 v[160:163], v191 offset:36864
	v_readfirstlane_b32 s34, v166
	s_cmp_lt_u32 s34, 0x100
	s_cbranch_scc1 .Lstg_LBB01032_1
	s_add_u32 s34, s4, s20
	s_addc_u32 s35, s5, s21
	s_mov_b32 m0, s28
	v_lshl_add_u64 v[164:165], v[136:137], 0, s[34:35]
	global_load_lds_dwordx4 v[164:165], off
	s_add_u32 s34, s4, vcc_lo
	s_addc_u32 s35, s5, vcc_hi
	s_add_u32 m0, s28, 0x2000
	v_lshl_add_u64 v[164:165], v[136:137], 0, s[34:35]
	global_load_lds_dwordx4 v[164:165], off
	s_add_u32 s34, s4, s68
	s_addc_u32 s35, s5, s69
	s_add_u32 m0, s28, 0x4000
	v_lshl_add_u64 v[164:165], v[136:137], 0, s[34:35]
	global_load_lds_dwordx4 v[164:165], off
	s_add_u32 s34, s4, s88
	s_addc_u32 s35, s5, s89
	s_add_u32 m0, s28, 0x6000
	v_lshl_add_u64 v[164:165], v[136:137], 0, s[34:35]
	global_load_lds_dwordx4 v[164:165], off
	s_add_u32 s34, s4, 0xe00080
	s_addc_u32 s35, s5, 0
	s_add_u32 m0, s28, 0x8000
	v_lshl_add_u64 v[164:165], v[138:139], 0, s[34:35]
	global_load_lds_dwordx4 v[164:165], off
	s_add_u32 s34, s4, 0xe20080
	s_addc_u32 s35, s5, 0
	s_add_u32 m0, s28, 0xa000
	v_lshl_add_u64 v[164:165], v[138:139], 0, s[34:35]
	global_load_lds_dwordx4 v[164:165], off
	s_add_u32 s34, s4, 0xe40080
	s_addc_u32 s35, s5, 0
	s_add_u32 m0, s28, 0xc000
	v_lshl_add_u64 v[164:165], v[138:139], 0, s[34:35]
	global_load_lds_dwordx4 v[164:165], off
	s_add_u32 s34, s4, 0xe60080
	s_addc_u32 s35, s5, 0
	s_add_u32 m0, s28, 0xe000
	v_lshl_add_u64 v[164:165], v[138:139], 0, s[34:35]
	global_load_lds_dwordx4 v[164:165], off
; template <int EPI, int AMAP, int KOFFMODE, int K>
; __device__ __forceinline__ void gemm_phase(unsigned char* smem, const bf16_t* A, int lda, const bf16_t* Bt, int NT, const EpiArgs& ea) {
;     ...
;             for (int s = 0; s < 4; ++s) {
;                 if (s < 3) {
;                     const int o_ = (((2 * (s + 1)) ^ yz) & 7) * 16;
;                     fb[(s + 1) & 1][0] = *(const bf16x8*)(Bc + o_);
;                     fb[(s + 1) & 1][1] = *(const bf16x8*)(Bc + 32 * 128 + o_);
; #pragma unroll
;                     for (int i = 0; i < 4; ++i) fa[(s + 1) & 1][i] = *(const bf16x8*)(Ac + i * 32 * 128 + o_);
;                 }
; #pragma unroll
;                 for (int i = 0; i < 4; ++i) {
;                     acc[i][0] = __builtin_amdgcn_mfma_f32_32x32x16_bf16(fa[s & 1][i], fb[s & 1][0], acc[i][0], 0, 0, 0);
;                     acc[i][1] = __builtin_amdgcn_mfma_f32_32x32x16_bf16(fa[s & 1][i], fb[s & 1][1], acc[i][1], 0, 0, 0);
;                 }
;                 __builtin_amdgcn_sched_barrier(0);
;             }
;             if (kt + 1 < nk) asm volatile("s_waitcnt vmcnt(0)" ::: "memory");
;             __builtin_amdgcn_s_barrier();
;             cur ^= 1;
;         }
.Lstg_LBB01032_1:
	s_waitcnt lgkmcnt(5)
	v_mfma_f32_32x32x16_bf16 v[114:129], v[192:195], v[208:211], v[114:129]
	v_mfma_f32_32x32x16_bf16 v[98:113], v[192:195], v[212:215], v[98:113]
	ds_read_b128 v[192:195], v0
	s_waitcnt lgkmcnt(5)
	v_mfma_f32_32x32x16_bf16 v[82:97], v[196:199], v[208:211], v[82:97]
	v_mfma_f32_32x32x16_bf16 v[66:81], v[196:199], v[212:215], v[66:81]
	ds_read_b128 v[196:199], v0 offset:4096
	s_waitcnt lgkmcnt(5)
	v_mfma_f32_32x32x16_bf16 v[50:65], v[200:203], v[208:211], v[50:65]
	v_mfma_f32_32x32x16_bf16 v[34:49], v[200:203], v[212:215], v[34:49]
	ds_read_b128 v[200:203], v0 offset:8192
	s_waitcnt lgkmcnt(5)
	v_mfma_f32_32x32x16_bf16 v[18:33], v[204:207], v[208:211], v[18:33]
	v_mfma_f32_32x32x16_bf16 v[2:17], v[204:207], v[212:215], v[2:17]
	ds_read_b128 v[204:207], v0 offset:12288
	v_add3_u32 v191, s15, v151, v150
	v_add_u32_e32 v191, v191, v155
	v_add3_u32 v0, s15, v149, v150
	v_add_u32_e32 v0, v0, v155
	ds_read_b128 v[208:211], v191 offset:32768
	ds_read_b128 v[212:215], v191 offset:36864
	s_waitcnt lgkmcnt(5)
	v_mfma_f32_32x32x16_bf16 v[114:129], v[192:195], v[156:159], v[114:129]
	v_mfma_f32_32x32x16_bf16 v[98:113], v[192:195], v[160:163], v[98:113]
	ds_read_b128 v[192:195], v0
	s_waitcnt lgkmcnt(5)
	v_mfma_f32_32x32x16_bf16 v[82:97], v[196:199], v[156:159], v[82:97]
	v_mfma_f32_32x32x16_bf16 v[66:81], v[196:199], v[160:163], v[66:81]
	ds_read_b128 v[196:199], v0 offset:4096
	s_waitcnt lgkmcnt(5)
	v_mfma_f32_32x32x16_bf16 v[50:65], v[200:203], v[156:159], v[50:65]
	v_mfma_f32_32x32x16_bf16 v[34:49], v[200:203], v[160:163], v[34:49]
	ds_read_b128 v[200:203], v0 offset:8192
	s_waitcnt lgkmcnt(5)
	v_mfma_f32_32x32x16_bf16 v[18:33], v[204:207], v[156:159], v[18:33]
	v_mfma_f32_32x32x16_bf16 v[2:17], v[204:207], v[160:163], v[2:17]
	ds_read_b128 v[204:207], v0 offset:12288
	s_waitcnt lgkmcnt(3)
	v_mfma_f32_32x32x16_bf16 v[114:129], v[192:195], v[208:211], v[114:129]
	v_mfma_f32_32x32x16_bf16 v[98:113], v[192:195], v[212:215], v[98:113]
	s_waitcnt lgkmcnt(2)
	v_mfma_f32_32x32x16_bf16 v[82:97], v[196:199], v[208:211], v[82:97]
	v_mfma_f32_32x32x16_bf16 v[66:81], v[196:199], v[212:215], v[66:81]
	s_waitcnt lgkmcnt(0)
	s_waitcnt vmcnt(0)
	s_barrier
	v_add3_u32 v191, s14, v151, v150
	v_add_u32_e32 v191, v191, v152
	v_add3_u32 v0, s14, v149, v150
	v_add_u32_e32 v0, v0, v152
	ds_read_b128 v[156:159], v191 offset:32768
	ds_read_b128 v[160:163], v191 offset:36864
	ds_read_b128 v[192:195], v0
	ds_read_b128 v[196:199], v0 offset:4096
	v_mfma_f32_32x32x16_bf16 v[50:65], v[200:203], v[208:211], v[50:65]
	v_mfma_f32_32x32x16_bf16 v[34:49], v[200:203], v[212:215], v[34:49]
	ds_read_b128 v[200:203], v0 offset:8192
	v_mfma_f32_32x32x16_bf16 v[18:33], v[204:207], v[208:211], v[18:33]
	v_mfma_f32_32x32x16_bf16 v[2:17], v[204:207], v[212:215], v[2:17]
	ds_read_b128 v[204:207], v0 offset:12288
	s_xor_b32 s15, s11, 1
	s_add_u32 s4, s4, 0x80
	s_addc_u32 s5, s5, 0
	s_cmpk_eq_i32 s4, 0x780
	s_cbranch_scc0 .LBB0_1032
	s_waitcnt lgkmcnt(0)
	s_andn2_b64 vcc, exec, s[2:3]
	s_lshl_b32 s2, s15, 16
	s_cbranch_vccnz .LBB0_1024
	v_add_u32_e32 v136, s10, v143
	s_xor_b32 s3, s2, 0x10000
	v_ashrrev_i32_e32 v137, 31, v136
	v_add_u32_e32 v138, s9, v143
	v_add_u32_e32 v0, s3, v144
	v_lshlrev_b64 v[136:137], 11, v[136:137]
	v_ashrrev_i32_e32 v139, 31, v138
	v_add_u32_e32 v156, 0x8000, v0
	v_readfirstlane_b32 s3, v0
	v_lshlrev_b64 v[138:139], 11, v[138:139]
	v_lshl_add_u64 v[136:137], v[130:131], 0, v[136:137]
	s_mov_b32 m0, s3
	v_readfirstlane_b32 s3, v156
	v_add_u32_e32 v158, 0x2000, v0
	v_lshl_add_u64 v[138:139], v[132:133], 0, v[138:139]
	global_load_lds_dwordx4 v[136:137], off
	s_mov_b32 m0, s3
	s_mov_b64 s[4:5], 0x20000
	v_readfirstlane_b32 s3, v158
	v_add_u32_e32 v158, 0xa000, v0
	global_load_lds_dwordx4 v[138:139], off
	v_lshl_add_u64 v[156:157], v[136:137], 0, s[4:5]
	s_mov_b32 m0, s3
	v_readfirstlane_b32 s3, v158
	v_add_u32_e32 v158, 0x4000, v0
	global_load_lds_dwordx4 v[156:157], off
	v_lshl_add_u64 v[156:157], v[138:139], 0, s[4:5]
	s_mov_b32 m0, s3
	s_mov_b64 s[4:5], 0x40000
	v_readfirstlane_b32 s3, v158
	v_add_u32_e32 v158, 0xc000, v0
	global_load_lds_dwordx4 v[156:157], off
	v_lshl_add_u64 v[156:157], v[136:137], 0, s[4:5]
	s_mov_b32 m0, s3
	v_readfirstlane_b32 s3, v158
	global_load_lds_dwordx4 v[156:157], off
	v_lshl_add_u64 v[156:157], v[138:139], 0, s[4:5]
	s_mov_b32 m0, s3
	s_mov_b64 s[4:5], 0x60000
	global_load_lds_dwordx4 v[156:157], off
	v_add_u32_e32 v156, 0x6000, v0
	v_add_u32_e32 v0, 0xe000, v0
	v_readfirstlane_b32 s3, v156
	v_lshl_add_u64 v[136:137], v[136:137], 0, s[4:5]
	s_mov_b32 m0, s3
	v_readfirstlane_b32 s3, v0
	global_load_lds_dwordx4 v[136:137], off
	v_lshl_add_u64 v[136:137], v[138:139], 0, s[4:5]
	s_mov_b32 m0, s3
	s_nop 0
	global_load_lds_dwordx4 v[136:137], off
	s_branch .LBB0_1024

; template <int EPI, int AMAP, int KOFFMODE, int K>
; __device__ __forceinline__ void gemm_phase(unsigned char* smem, const bf16_t* A, int lda, const bf16_t* Bt, int NT, const EpiArgs& ea) {
;     ...
;         for (int kt = 0; kt < nk; ++kt) {
;             if (kt + 1 < nk) GEMM_DMA(m0, n0, kt + 1, cur ^ 1);
;             else if (have_next) GEMM_DMA(m0n, n0n, 0, cur ^ 1);
;             const unsigned char* Ac = smem + cur * STGB + (wm * 128 + l31) * 128;
;             const unsigned char* Bc = smem + cur * STGB + 32768 + (wn * 64 + l31) * 128;
;             bf16x8 fa[2][4], fb[2][2];
;             fb[0][0] = *(const bf16x8*)(Bc + (((0) ^ yz) & 7) * 16);
;             fb[0][1] = *(const bf16x8*)(Bc + 32 * 128 + (((0) ^ yz) & 7) * 16);
; #pragma unroll
;             for (int i = 0; i < 4; ++i) fa[0][i] = *(const bf16x8*)(Ac + i * 32 * 128 + (((0) ^ yz) & 7) * 16);
; #pragma unroll
;             for (int s = 0; s < 4; ++s) {
;                 if (s < 3) {
;                     const int o_ = (((2 * (s + 1)) ^ yz) & 7) * 16;
;                     fb[(s + 1) & 1][0] = *(const bf16x8*)(Bc + o_);
;                     fb[(s + 1) & 1][1] = *(const bf16x8*)(Bc + 32 * 128 + o_);
; #pragma unroll
;                     for (int i = 0; i < 4; ++i) fa[(s + 1) & 1][i] = *(const bf16x8*)(Ac + i * 32 * 128 + o_);
;                 }
; #pragma unroll
;                 for (int i = 0; i < 4; ++i) {
;                     acc[i][0] = __builtin_amdgcn_mfma_f32_32x32x16_bf16(fa[s & 1][i], fb[s & 1][0], acc[i][0], 0, 0, 0);
;                     acc[i][1] = __builtin_amdgcn_mfma_f32_32x32x16_bf16(fa[s & 1][i], fb[s & 1][1], acc[i][1], 0, 0, 0);
;                 }
;                 __builtin_amdgcn_sched_barrier(0);
;             }
;             if (kt + 1 < nk) asm volatile("s_waitcnt vmcnt(0)" ::: "memory");
;             __builtin_amdgcn_s_barrier();
.LBB0_1161:
	s_mov_b32 s13, s34
	s_lshl_b32 s36, s13, 16
	s_xor_b32 s28, s36, 0x10000
	v_readfirstlane_b32 vcc_lo, v144
	s_nop 0
	s_add_u32 vcc_lo, vcc_lo, s28
	v_add3_u32 v191, s36, v151, v150
	v_add_u32_e32 v191, v191, v153
	v_add3_u32 v0, s36, v149, v150
	v_add_u32_e32 v0, v0, v153
	ds_read_b128 v[208:211], v191 offset:32768
	ds_read_b128 v[212:215], v191 offset:36864
	v_readfirstlane_b32 s34, v166
	s_cmp_lt_u32 s34, 0x100
	s_cbranch_scc0 .Lstg_LBB01161_0
	s_add_u32 s34, s8, 0x4100080
	s_addc_u32 s35, s9, 0
	s_mov_b32 m0, vcc_lo
	v_lshl_add_u64 v[164:165], v[136:137], 0, s[34:35]
	global_load_lds_dwordx4 v[164:165], off
	s_add_u32 s34, s8, 0x4158080
	s_addc_u32 s35, s9, 0
	s_add_u32 m0, vcc_lo, 0x2000
	v_lshl_add_u64 v[164:165], v[136:137], 0, s[34:35]
	global_load_lds_dwordx4 v[164:165], off
	s_add_u32 s34, s8, 0x41b0080
	s_addc_u32 s35, s9, 0
	s_add_u32 m0, vcc_lo, 0x4000
	v_lshl_add_u64 v[164:165], v[136:137], 0, s[34:35]
	global_load_lds_dwordx4 v[164:165], off
	s_add_u32 s34, s8, 0x4208080
	s_addc_u32 s35, s9, 0
	s_add_u32 m0, vcc_lo, 0x6000
	v_lshl_add_u64 v[164:165], v[136:137], 0, s[34:35]
	global_load_lds_dwordx4 v[164:165], off
	s_add_u32 s34, s8, 0x1900080
	s_addc_u32 s35, s9, 0
	s_add_u32 m0, vcc_lo, 0x8000
	v_lshl_add_u64 v[164:165], v[138:139], 0, s[34:35]
	global_load_lds_dwordx4 v[164:165], off
	s_add_u32 s34, s8, 0x1958080
	s_addc_u32 s35, s9, 0
	s_add_u32 m0, vcc_lo, 0xa000
	v_lshl_add_u64 v[164:165], v[138:139], 0, s[34:35]
	global_load_lds_dwordx4 v[164:165], off
	s_add_u32 s34, s8, 0x19b0080
	s_addc_u32 s35, s9, 0
	s_add_u32 m0, vcc_lo, 0xc000
	v_lshl_add_u64 v[164:165], v[138:139], 0, s[34:35]
	global_load_lds_dwordx4 v[164:165], off
	s_add_u32 s34, s8, 0x1a08080
	s_addc_u32 s35, s9, 0
	s_add_u32 m0, vcc_lo, 0xe000
	v_lshl_add_u64 v[164:165], v[138:139], 0, s[34:35]
	global_load_lds_dwordx4 v[164:165], off
.Lstg_LBB01161_0:
	s_waitcnt lgkmcnt(5)
	v_mfma_f32_32x32x16_bf16 v[114:129], v[192:195], v[156:159], v[114:129]
	v_mfma_f32_32x32x16_bf16 v[98:113], v[192:195], v[160:163], v[98:113]
	ds_read_b128 v[192:195], v0
	s_waitcnt lgkmcnt(5)
	v_mfma_f32_32x32x16_bf16 v[82:97], v[196:199], v[156:159], v[82:97]
	v_mfma_f32_32x32x16_bf16 v[66:81], v[196:199], v[160:163], v[66:81]
	ds_read_b128 v[196:199], v0 offset:4096
	s_waitcnt lgkmcnt(5)
	v_mfma_f32_32x32x16_bf16 v[50:65], v[200:203], v[156:159], v[50:65]
	v_mfma_f32_32x32x16_bf16 v[34:49], v[200:203], v[160:163], v[34:49]
	ds_read_b128 v[200:203], v0 offset:8192
	s_waitcnt lgkmcnt(5)
	v_mfma_f32_32x32x16_bf16 v[18:33], v[204:207], v[156:159], v[18:33]
	v_mfma_f32_32x32x16_bf16 v[2:17], v[204:207], v[160:163], v[2:17]
	ds_read_b128 v[204:207], v0 offset:12288
	v_add3_u32 v191, s36, v151, v150
	v_add_u32_e32 v191, v191, v154
	v_add3_u32 v0, s36, v149, v150
	v_add_u32_e32 v0, v0, v154
	ds_read_b128 v[156:159], v191 offset:32768
	ds_read_b128 v[160:163], v191 offset:36864
	v_readfirstlane_b32 s34, v166
	s_cmp_lt_u32 s34, 0x100
	s_cbranch_scc1 .Lstg_LBB01161_1
	s_add_u32 s34, s8, 0x4100080
	s_addc_u32 s35, s9, 0
	s_mov_b32 m0, vcc_lo
	v_lshl_add_u64 v[164:165], v[136:137], 0, s[34:35]
	global_load_lds_dwordx4 v[164:165], off
	s_add_u32 s34, s8, 0x4158080
	s_addc_u32 s35, s9, 0
	s_add_u32 m0, vcc_lo, 0x2000
	v_lshl_add_u64 v[164:165], v[136:137], 0, s[34:35]
	global_load_lds_dwordx4 v[164:165], off
	s_add_u32 s34, s8, 0x41b0080
	s_addc_u32 s35, s9, 0
	s_add_u32 m0, vcc_lo, 0x4000
	v_lshl_add_u64 v[164:165], v[136:137], 0, s[34:35]
	global_load_lds_dwordx4 v[164:165], off
	s_add_u32 s34, s8, 0x4208080
	s_addc_u32 s35, s9, 0
	s_add_u32 m0, vcc_lo, 0x6000
	v_lshl_add_u64 v[164:165], v[136:137], 0, s[34:35]
	global_load_lds_dwordx4 v[164:165], off
	s_add_u32 s34, s8, 0x1900080
	s_addc_u32 s35, s9, 0
	s_add_u32 m0, vcc_lo, 0x8000
	v_lshl_add_u64 v[164:165], v[138:139], 0, s[34:35]
	global_load_lds_dwordx4 v[164:165], off
	s_add_u32 s34, s8, 0x1958080
	s_addc_u32 s35, s9, 0
	s_add_u32 m0, vcc_lo, 0xa000
	v_lshl_add_u64 v[164:165], v[138:139], 0, s[34:35]
	global_load_lds_dwordx4 v[164:165], off
	s_add_u32 s34, s8, 0x19b0080
	s_addc_u32 s35, s9, 0
	s_add_u32 m0, vcc_lo, 0xc000
	v_lshl_add_u64 v[164:165], v[138:139], 0, s[34:35]
	global_load_lds_dwordx4 v[164:165], off
	s_add_u32 s34, s8, 0x1a08080
	s_addc_u32 s35, s9, 0
	s_add_u32 m0, vcc_lo, 0xe000
	v_lshl_add_u64 v[164:165], v[138:139], 0, s[34:35]
	global_load_lds_dwordx4 v[164:165], off
; template <int EPI, int AMAP, int KOFFMODE, int K>
; __device__ __forceinline__ void gemm_phase(unsigned char* smem, const bf16_t* A, int lda, const bf16_t* Bt, int NT, const EpiArgs& ea) {
;     ...
;             for (int s = 0; s < 4; ++s) {
;                 if (s < 3) {
;                     const int o_ = (((2 * (s + 1)) ^ yz) & 7) * 16;
;                     fb[(s + 1) & 1][0] = *(const bf16x8*)(Bc + o_);
;                     fb[(s + 1) & 1][1] = *(const bf16x8*)(Bc + 32 * 128 + o_);
; #pragma unroll
;                     for (int i = 0; i < 4; ++i) fa[(s + 1) & 1][i] = *(const bf16x8*)(Ac + i * 32 * 128 + o_);
;                 }
; #pragma unroll
;                 for (int i = 0; i < 4; ++i) {
;                     acc[i][0] = __builtin_amdgcn_mfma_f32_32x32x16_bf16(fa[s & 1][i], fb[s & 1][0], acc[i][0], 0, 0, 0);
;                     acc[i][1] = __builtin_amdgcn_mfma_f32_32x32x16_bf16(fa[s & 1][i], fb[s & 1][1], acc[i][1], 0, 0, 0);
;                 }
;                 __builtin_amdgcn_sched_barrier(0);
;             }
;             if (kt + 1 < nk) asm volatile("s_waitcnt vmcnt(0)" ::: "memory");
;             __builtin_amdgcn_s_barrier();
;             cur ^= 1;
;         }
.Lstg_LBB01161_1:
	s_waitcnt lgkmcnt(5)
	v_mfma_f32_32x32x16_bf16 v[114:129], v[192:195], v[208:211], v[114:129]
	v_mfma_f32_32x32x16_bf16 v[98:113], v[192:195], v[212:215], v[98:113]
	ds_read_b128 v[192:195], v0
	s_waitcnt lgkmcnt(5)
	v_mfma_f32_32x32x16_bf16 v[82:97], v[196:199], v[208:211], v[82:97]
	v_mfma_f32_32x32x16_bf16 v[66:81], v[196:199], v[212:215], v[66:81]
	ds_read_b128 v[196:199], v0 offset:4096
	s_waitcnt lgkmcnt(5)
	v_mfma_f32_32x32x16_bf16 v[50:65], v[200:203], v[208:211], v[50:65]
	v_mfma_f32_32x32x16_bf16 v[34:49], v[200:203], v[212:215], v[34:49]
	ds_read_b128 v[200:203], v0 offset:8192
	s_waitcnt lgkmcnt(5)
	v_mfma_f32_32x32x16_bf16 v[18:33], v[204:207], v[208:211], v[18:33]
	v_mfma_f32_32x32x16_bf16 v[2:17], v[204:207], v[212:215], v[2:17]
	ds_read_b128 v[204:207], v0 offset:12288
	v_add3_u32 v191, s36, v151, v150
	v_add_u32_e32 v191, v191, v155
	v_add3_u32 v0, s36, v149, v150
	v_add_u32_e32 v0, v0, v155
	ds_read_b128 v[208:211], v191 offset:32768
	ds_read_b128 v[212:215], v191 offset:36864
	s_waitcnt lgkmcnt(5)
	v_mfma_f32_32x32x16_bf16 v[114:129], v[192:195], v[156:159], v[114:129]
	v_mfma_f32_32x32x16_bf16 v[98:113], v[192:195], v[160:163], v[98:113]
	ds_read_b128 v[192:195], v0
	s_waitcnt lgkmcnt(5)
	v_mfma_f32_32x32x16_bf16 v[82:97], v[196:199], v[156:159], v[82:97]
	v_mfma_f32_32x32x16_bf16 v[66:81], v[196:199], v[160:163], v[66:81]
	ds_read_b128 v[196:199], v0 offset:4096
	s_waitcnt lgkmcnt(5)
	v_mfma_f32_32x32x16_bf16 v[50:65], v[200:203], v[156:159], v[50:65]
	v_mfma_f32_32x32x16_bf16 v[34:49], v[200:203], v[160:163], v[34:49]
	ds_read_b128 v[200:203], v0 offset:8192
	s_waitcnt lgkmcnt(5)
	v_mfma_f32_32x32x16_bf16 v[18:33], v[204:207], v[156:159], v[18:33]
	v_mfma_f32_32x32x16_bf16 v[2:17], v[204:207], v[160:163], v[2:17]
	ds_read_b128 v[204:207], v0 offset:12288
	s_waitcnt lgkmcnt(3)
	v_mfma_f32_32x32x16_bf16 v[114:129], v[192:195], v[208:211], v[114:129]
	v_mfma_f32_32x32x16_bf16 v[98:113], v[192:195], v[212:215], v[98:113]
	s_waitcnt lgkmcnt(2)
	v_mfma_f32_32x32x16_bf16 v[82:97], v[196:199], v[208:211], v[82:97]
	v_mfma_f32_32x32x16_bf16 v[66:81], v[196:199], v[212:215], v[66:81]
	s_waitcnt lgkmcnt(0)
	s_waitcnt vmcnt(0)
	s_barrier
	v_add3_u32 v191, s28, v151, v150
	v_add_u32_e32 v191, v191, v152
	v_add3_u32 v0, s28, v149, v150
	v_add_u32_e32 v0, v0, v152
	ds_read_b128 v[156:159], v191 offset:32768
	ds_read_b128 v[160:163], v191 offset:36864
	ds_read_b128 v[192:195], v0
	ds_read_b128 v[196:199], v0 offset:4096
	v_mfma_f32_32x32x16_bf16 v[50:65], v[200:203], v[208:211], v[50:65]
	v_mfma_f32_32x32x16_bf16 v[34:49], v[200:203], v[212:215], v[34:49]
	ds_read_b128 v[200:203], v0 offset:8192
	v_mfma_f32_32x32x16_bf16 v[18:33], v[204:207], v[208:211], v[18:33]
	v_mfma_f32_32x32x16_bf16 v[2:17], v[204:207], v[212:215], v[2:17]
	ds_read_b128 v[204:207], v0 offset:12288
	s_xor_b32 s34, s13, 1
	s_add_u32 s8, s8, 0x80
	s_addc_u32 s9, s9, 0
	s_cmpk_eq_i32 s8, 0x1580
	s_cbranch_scc0 .LBB0_1161
	s_waitcnt lgkmcnt(0)
	s_andn2_b64 vcc, exec, s[2:3]
	s_lshl_b32 s2, s34, 16
	s_cbranch_vccnz .LBB0_1153
	v_add_u32_e32 v0, s12, v143
	v_add_u32_e32 v136, s11, v143
	s_movk_i32 s3, 0x1600
	v_mad_i64_i32 v[136:137], s[8:9], v136, s3, v[132:133]
	v_mad_i64_i32 v[138:139], s[8:9], v0, s3, v[130:131]
	s_xor_b32 s3, s2, 0x10000
	v_add_u32_e32 v0, s3, v144
	v_add_u32_e32 v156, 0x8000, v0
	v_readfirstlane_b32 s3, v0
	s_mov_b32 m0, s3
	v_readfirstlane_b32 s3, v156
	v_add_u32_e32 v158, 0x2000, v0
	global_load_lds_dwordx4 v[138:139], off
	s_mov_b32 m0, s3
	s_mov_b64 s[8:9], 0x58000
	v_readfirstlane_b32 s3, v158
	v_add_u32_e32 v158, 0xa000, v0
	global_load_lds_dwordx4 v[136:137], off
	v_lshl_add_u64 v[156:157], v[138:139], 0, s[8:9]
	s_mov_b32 m0, s3
	v_readfirstlane_b32 s3, v158
	v_add_u32_e32 v158, 0x4000, v0
	global_load_lds_dwordx4 v[156:157], off
	v_lshl_add_u64 v[156:157], v[136:137], 0, s[8:9]
	s_mov_b32 m0, s3
	s_mov_b64 s[8:9], 0xb0000
	v_readfirstlane_b32 s3, v158
	v_add_u32_e32 v158, 0xc000, v0
	global_load_lds_dwordx4 v[156:157], off
	v_lshl_add_u64 v[156:157], v[138:139], 0, s[8:9]
	s_mov_b32 m0, s3
	v_readfirstlane_b32 s3, v158
	global_load_lds_dwordx4 v[156:157], off
	v_lshl_add_u64 v[156:157], v[136:137], 0, s[8:9]
	s_mov_b32 m0, s3
	s_mov_b64 s[8:9], 0x108000
	global_load_lds_dwordx4 v[156:157], off
	v_add_u32_e32 v156, 0x6000, v0
	v_add_u32_e32 v0, 0xe000, v0
	v_readfirstlane_b32 s3, v156
	v_lshl_add_u64 v[138:139], v[138:139], 0, s[8:9]
	s_mov_b32 m0, s3
	v_readfirstlane_b32 s3, v0
	global_load_lds_dwordx4 v[138:139], off
	v_lshl_add_u64 v[136:137], v[136:137], 0, s[8:9]
	s_mov_b32 m0, s3
	s_nop 0
	global_load_lds_dwordx4 v[136:137], off
	s_branch .LBB0_1153

; template <int EPI, int AMAP, int KOFFMODE, int K>
; __device__ __forceinline__ void gemm_phase(unsigned char* smem, const bf16_t* A, int lda, const bf16_t* Bt, int NT, const EpiArgs& ea) {
;     ...
;         for (int kt = 0; kt < nk; ++kt) {
;             if (kt + 1 < nk) GEMM_DMA(m0, n0, kt + 1, cur ^ 1);
;             else if (have_next) GEMM_DMA(m0n, n0n, 0, cur ^ 1);
;             const unsigned char* Ac = smem + cur * STGB + (wm * 128 + l31) * 128;
;             const unsigned char* Bc = smem + cur * STGB + 32768 + (wn * 64 + l31) * 128;
;             bf16x8 fa[2][4], fb[2][2];
;             fb[0][0] = *(const bf16x8*)(Bc + (((0) ^ yz) & 7) * 16);
;             fb[0][1] = *(const bf16x8*)(Bc + 32 * 128 + (((0) ^ yz) & 7) * 16);
; #pragma unroll
;             for (int i = 0; i < 4; ++i) fa[0][i] = *(const bf16x8*)(Ac + i * 32 * 128 + (((0) ^ yz) & 7) * 16);
; #pragma unroll
;             for (int s = 0; s < 4; ++s) {
;                 if (s < 3) {
;                     const int o_ = (((2 * (s + 1)) ^ yz) & 7) * 16;
;                     fb[(s + 1) & 1][0] = *(const bf16x8*)(Bc + o_);
;                     fb[(s + 1) & 1][1] = *(const bf16x8*)(Bc + 32 * 128 + o_);
; #pragma unroll
;                     for (int i = 0; i < 4; ++i) fa[(s + 1) & 1][i] = *(const bf16x8*)(Ac + i * 32 * 128 + o_);
;                 }
; #pragma unroll
;                 for (int i = 0; i < 4; ++i) {
;                     acc[i][0] = __builtin_amdgcn_mfma_f32_32x32x16_bf16(fa[s & 1][i], fb[s & 1][0], acc[i][0], 0, 0, 0);
;                     acc[i][1] = __builtin_amdgcn_mfma_f32_32x32x16_bf16(fa[s & 1][i], fb[s & 1][1], acc[i][1], 0, 0, 0);
;                 }
;                 __builtin_amdgcn_sched_barrier(0);
;             }
;             if (kt + 1 < nk) asm volatile("s_waitcnt vmcnt(0)" ::: "memory");
;             __builtin_amdgcn_s_barrier();
.LBB0_1429:
	s_mov_b32 s9, s13
	s_lshl_b32 s13, s9, 16
	s_xor_b32 s12, s13, 0x10000
	v_readfirstlane_b32 vcc_lo, v143
	s_nop 0
	s_add_u32 vcc_lo, vcc_lo, s12
	v_add3_u32 v155, s13, v150, v149
	v_add_u32_e32 v155, v155, v152
	v_add3_u32 v0, s13, v147, v149
	v_add_u32_e32 v0, v0, v152
	ds_read_b128 v[208:211], v155 offset:32768
	ds_read_b128 v[212:215], v155 offset:36864
	v_readfirstlane_b32 s14, v166
	s_cmp_lt_u32 s14, 0x100
	s_cbranch_scc0 .Lstg_LBB01429_0
	s_add_u32 s14, s4, 0xe380080
	s_addc_u32 s15, s5, 0
	s_mov_b32 m0, vcc_lo
	v_lshl_add_u64 v[164:165], v[136:137], 0, s[14:15]
	global_load_lds_dwordx4 v[164:165], off
	s_add_u32 s14, s4, 0xe3a0080
	s_addc_u32 s15, s5, 0
	s_add_u32 m0, vcc_lo, 0x2000
	v_lshl_add_u64 v[164:165], v[136:137], 0, s[14:15]
	global_load_lds_dwordx4 v[164:165], off
	s_add_u32 s14, s4, 0xe3c0080
	s_addc_u32 s15, s5, 0
	s_add_u32 m0, vcc_lo, 0x4000
	v_lshl_add_u64 v[164:165], v[136:137], 0, s[14:15]
	global_load_lds_dwordx4 v[164:165], off
	s_add_u32 s14, s4, 0xe3e0080
	s_addc_u32 s15, s5, 0
	s_add_u32 m0, vcc_lo, 0x6000
	v_lshl_add_u64 v[164:165], v[136:137], 0, s[14:15]
	global_load_lds_dwordx4 v[164:165], off
	s_add_u32 s14, s4, s20
	s_addc_u32 s15, s5, s21
	s_add_u32 m0, vcc_lo, 0x8000
	v_lshl_add_u64 v[164:165], v[138:139], 0, s[14:15]
	global_load_lds_dwordx4 v[164:165], off
	s_add_u32 s14, s4, 0x820080
	s_addc_u32 s15, s5, 0
	s_add_u32 m0, vcc_lo, 0xa000
	v_lshl_add_u64 v[164:165], v[138:139], 0, s[14:15]
	global_load_lds_dwordx4 v[164:165], off
	s_add_u32 s14, s4, s68
	s_addc_u32 s15, s5, s69
	s_add_u32 m0, vcc_lo, 0xc000
	v_lshl_add_u64 v[164:165], v[138:139], 0, s[14:15]
	global_load_lds_dwordx4 v[164:165], off
	s_add_u32 s14, s4, 0x860080
	s_addc_u32 s15, s5, 0
	s_add_u32 m0, vcc_lo, 0xe000
	v_lshl_add_u64 v[164:165], v[138:139], 0, s[14:15]
	global_load_lds_dwordx4 v[164:165], off
.Lstg_LBB01429_0:
	s_waitcnt lgkmcnt(5)
	v_mfma_f32_32x32x16_bf16 v[114:129], v[192:195], v[156:159], v[114:129]
	v_mfma_f32_32x32x16_bf16 v[98:113], v[192:195], v[160:163], v[98:113]
	ds_read_b128 v[192:195], v0
	s_waitcnt lgkmcnt(5)
	v_mfma_f32_32x32x16_bf16 v[82:97], v[196:199], v[156:159], v[82:97]
	v_mfma_f32_32x32x16_bf16 v[66:81], v[196:199], v[160:163], v[66:81]
	ds_read_b128 v[196:199], v0 offset:4096
	s_waitcnt lgkmcnt(5)
	v_mfma_f32_32x32x16_bf16 v[50:65], v[200:203], v[156:159], v[50:65]
	v_mfma_f32_32x32x16_bf16 v[34:49], v[200:203], v[160:163], v[34:49]
	ds_read_b128 v[200:203], v0 offset:8192
	s_waitcnt lgkmcnt(5)
	v_mfma_f32_32x32x16_bf16 v[18:33], v[204:207], v[156:159], v[18:33]
	v_mfma_f32_32x32x16_bf16 v[2:17], v[204:207], v[160:163], v[2:17]
	ds_read_b128 v[204:207], v0 offset:12288
	v_add3_u32 v155, s13, v150, v149
	v_add_u32_e32 v155, v155, v153
	v_add3_u32 v0, s13, v147, v149
	v_add_u32_e32 v0, v0, v153
	ds_read_b128 v[156:159], v155 offset:32768
	ds_read_b128 v[160:163], v155 offset:36864
	v_readfirstlane_b32 s14, v166
	s_cmp_lt_u32 s14, 0x100
	s_cbranch_scc1 .Lstg_LBB01429_1
	s_add_u32 s14, s4, 0xe380080
	s_addc_u32 s15, s5, 0
	s_mov_b32 m0, vcc_lo
	v_lshl_add_u64 v[164:165], v[136:137], 0, s[14:15]
	global_load_lds_dwordx4 v[164:165], off
	s_add_u32 s14, s4, 0xe3a0080
	s_addc_u32 s15, s5, 0
	s_add_u32 m0, vcc_lo, 0x2000
	v_lshl_add_u64 v[164:165], v[136:137], 0, s[14:15]
	global_load_lds_dwordx4 v[164:165], off
	s_add_u32 s14, s4, 0xe3c0080
	s_addc_u32 s15, s5, 0
	s_add_u32 m0, vcc_lo, 0x4000
	v_lshl_add_u64 v[164:165], v[136:137], 0, s[14:15]
	global_load_lds_dwordx4 v[164:165], off
	s_add_u32 s14, s4, 0xe3e0080
	s_addc_u32 s15, s5, 0
	s_add_u32 m0, vcc_lo, 0x6000
	v_lshl_add_u64 v[164:165], v[136:137], 0, s[14:15]
	global_load_lds_dwordx4 v[164:165], off
	s_add_u32 s14, s4, s20
	s_addc_u32 s15, s5, s21
	s_add_u32 m0, vcc_lo, 0x8000
	v_lshl_add_u64 v[164:165], v[138:139], 0, s[14:15]
	global_load_lds_dwordx4 v[164:165], off
	s_add_u32 s14, s4, 0x820080
	s_addc_u32 s15, s5, 0
	s_add_u32 m0, vcc_lo, 0xa000
	v_lshl_add_u64 v[164:165], v[138:139], 0, s[14:15]
	global_load_lds_dwordx4 v[164:165], off
	s_add_u32 s14, s4, s68
	s_addc_u32 s15, s5, s69
	s_add_u32 m0, vcc_lo, 0xc000
	v_lshl_add_u64 v[164:165], v[138:139], 0, s[14:15]
	global_load_lds_dwordx4 v[164:165], off
	s_add_u32 s14, s4, 0x860080
	s_addc_u32 s15, s5, 0
	s_add_u32 m0, vcc_lo, 0xe000
	v_lshl_add_u64 v[164:165], v[138:139], 0, s[14:15]
	global_load_lds_dwordx4 v[164:165], off
; template <int EPI, int AMAP, int KOFFMODE, int K>
; __device__ __forceinline__ void gemm_phase(unsigned char* smem, const bf16_t* A, int lda, const bf16_t* Bt, int NT, const EpiArgs& ea) {
;     ...
;             for (int s = 0; s < 4; ++s) {
;                 if (s < 3) {
;                     const int o_ = (((2 * (s + 1)) ^ yz) & 7) * 16;
;                     fb[(s + 1) & 1][0] = *(const bf16x8*)(Bc + o_);
;                     fb[(s + 1) & 1][1] = *(const bf16x8*)(Bc + 32 * 128 + o_);
; #pragma unroll
;                     for (int i = 0; i < 4; ++i) fa[(s + 1) & 1][i] = *(const bf16x8*)(Ac + i * 32 * 128 + o_);
;                 }
; #pragma unroll
;                 for (int i = 0; i < 4; ++i) {
;                     acc[i][0] = __builtin_amdgcn_mfma_f32_32x32x16_bf16(fa[s & 1][i], fb[s & 1][0], acc[i][0], 0, 0, 0);
;                     acc[i][1] = __builtin_amdgcn_mfma_f32_32x32x16_bf16(fa[s & 1][i], fb[s & 1][1], acc[i][1], 0, 0, 0);
;                 }
;                 __builtin_amdgcn_sched_barrier(0);
;             }
;             if (kt + 1 < nk) asm volatile("s_waitcnt vmcnt(0)" ::: "memory");
;             __builtin_amdgcn_s_barrier();
;             cur ^= 1;
;         }
.Lstg_LBB01429_1:
	s_waitcnt lgkmcnt(5)
	v_mfma_f32_32x32x16_bf16 v[114:129], v[192:195], v[208:211], v[114:129]
	v_mfma_f32_32x32x16_bf16 v[98:113], v[192:195], v[212:215], v[98:113]
	ds_read_b128 v[192:195], v0
	s_waitcnt lgkmcnt(5)
	v_mfma_f32_32x32x16_bf16 v[82:97], v[196:199], v[208:211], v[82:97]
	v_mfma_f32_32x32x16_bf16 v[66:81], v[196:199], v[212:215], v[66:81]
	ds_read_b128 v[196:199], v0 offset:4096
	s_waitcnt lgkmcnt(5)
	v_mfma_f32_32x32x16_bf16 v[50:65], v[200:203], v[208:211], v[50:65]
	v_mfma_f32_32x32x16_bf16 v[34:49], v[200:203], v[212:215], v[34:49]
	ds_read_b128 v[200:203], v0 offset:8192
	s_waitcnt lgkmcnt(5)
	v_mfma_f32_32x32x16_bf16 v[18:33], v[204:207], v[208:211], v[18:33]
	v_mfma_f32_32x32x16_bf16 v[2:17], v[204:207], v[212:215], v[2:17]
	ds_read_b128 v[204:207], v0 offset:12288
	v_add3_u32 v155, s13, v150, v149
	v_add_u32_e32 v155, v155, v154
	v_add3_u32 v0, s13, v147, v149
	v_add_u32_e32 v0, v0, v154
	ds_read_b128 v[208:211], v155 offset:32768
	ds_read_b128 v[212:215], v155 offset:36864
	s_waitcnt lgkmcnt(5)
	v_mfma_f32_32x32x16_bf16 v[114:129], v[192:195], v[156:159], v[114:129]
	v_mfma_f32_32x32x16_bf16 v[98:113], v[192:195], v[160:163], v[98:113]
	ds_read_b128 v[192:195], v0
	s_waitcnt lgkmcnt(5)
	v_mfma_f32_32x32x16_bf16 v[82:97], v[196:199], v[156:159], v[82:97]
	v_mfma_f32_32x32x16_bf16 v[66:81], v[196:199], v[160:163], v[66:81]
	ds_read_b128 v[196:199], v0 offset:4096
	s_waitcnt lgkmcnt(5)
	v_mfma_f32_32x32x16_bf16 v[50:65], v[200:203], v[156:159], v[50:65]
	v_mfma_f32_32x32x16_bf16 v[34:49], v[200:203], v[160:163], v[34:49]
	ds_read_b128 v[200:203], v0 offset:8192
	s_waitcnt lgkmcnt(5)
	v_mfma_f32_32x32x16_bf16 v[18:33], v[204:207], v[156:159], v[18:33]
	v_mfma_f32_32x32x16_bf16 v[2:17], v[204:207], v[160:163], v[2:17]
	ds_read_b128 v[204:207], v0 offset:12288
	s_waitcnt lgkmcnt(3)
	v_mfma_f32_32x32x16_bf16 v[114:129], v[192:195], v[208:211], v[114:129]
	v_mfma_f32_32x32x16_bf16 v[98:113], v[192:195], v[212:215], v[98:113]
	s_waitcnt lgkmcnt(2)
	v_mfma_f32_32x32x16_bf16 v[82:97], v[196:199], v[208:211], v[82:97]
	v_mfma_f32_32x32x16_bf16 v[66:81], v[196:199], v[212:215], v[66:81]
	s_waitcnt lgkmcnt(0)
	s_waitcnt vmcnt(0)
	s_barrier
	v_add3_u32 v155, s12, v150, v149
	v_add_u32_e32 v155, v155, v151
	v_add3_u32 v0, s12, v147, v149
	v_add_u32_e32 v0, v0, v151
	ds_read_b128 v[156:159], v155 offset:32768
	ds_read_b128 v[160:163], v155 offset:36864
	ds_read_b128 v[192:195], v0
	ds_read_b128 v[196:199], v0 offset:4096
	v_mfma_f32_32x32x16_bf16 v[50:65], v[200:203], v[208:211], v[50:65]
	v_mfma_f32_32x32x16_bf16 v[34:49], v[200:203], v[212:215], v[34:49]
	ds_read_b128 v[200:203], v0 offset:8192
	v_mfma_f32_32x32x16_bf16 v[18:33], v[204:207], v[208:211], v[18:33]
	v_mfma_f32_32x32x16_bf16 v[2:17], v[204:207], v[212:215], v[2:17]
	ds_read_b128 v[204:207], v0 offset:12288
	s_xor_b32 s13, s9, 1
	s_add_u32 s4, s4, 0x80
	s_addc_u32 s5, s5, 0
	s_cmpk_eq_i32 s4, 0x780
	s_cbranch_scc0 .LBB0_1429
	s_waitcnt lgkmcnt(0)
	s_andn2_b64 vcc, exec, s[2:3]
	s_lshl_b32 s2, s13, 16
	s_cbranch_vccnz .LBB0_1421
	v_add_u32_e32 v136, s8, v142
	s_xor_b32 s3, s2, 0x10000
	v_ashrrev_i32_e32 v137, 31, v136
	v_add_u32_e32 v138, s7, v142
	v_add_u32_e32 v0, s3, v143
	v_lshlrev_b64 v[136:137], 11, v[136:137]
	v_ashrrev_i32_e32 v139, 31, v138
	v_add_u32_e32 v155, 0x8000, v0
	v_readfirstlane_b32 s3, v0
	v_lshlrev_b64 v[138:139], 11, v[138:139]
	v_lshl_add_u64 v[136:137], v[130:131], 0, v[136:137]
	s_mov_b32 m0, s3
	v_readfirstlane_b32 s3, v155
	v_add_u32_e32 v155, 0x2000, v0
	v_lshl_add_u64 v[138:139], v[132:133], 0, v[138:139]
	global_load_lds_dwordx4 v[136:137], off
	s_mov_b32 m0, s3
	s_mov_b64 s[4:5], 0x20000
	v_readfirstlane_b32 s3, v155
	v_add_u32_e32 v155, 0xa000, v0
	global_load_lds_dwordx4 v[138:139], off
	v_lshl_add_u64 v[156:157], v[136:137], 0, s[4:5]
	s_mov_b32 m0, s3
	v_readfirstlane_b32 s3, v155
	v_add_u32_e32 v155, 0x4000, v0
	global_load_lds_dwordx4 v[156:157], off
	v_lshl_add_u64 v[156:157], v[138:139], 0, s[4:5]
	s_mov_b32 m0, s3
	s_mov_b64 s[4:5], 0x40000
	v_readfirstlane_b32 s3, v155
	v_add_u32_e32 v155, 0xc000, v0
	global_load_lds_dwordx4 v[156:157], off
	v_lshl_add_u64 v[156:157], v[136:137], 0, s[4:5]
	s_mov_b32 m0, s3
	v_readfirstlane_b32 s3, v155
	v_add_u32_e32 v155, 0x6000, v0
	global_load_lds_dwordx4 v[156:157], off
	v_lshl_add_u64 v[156:157], v[138:139], 0, s[4:5]
	s_mov_b32 m0, s3
	s_mov_b64 s[4:5], 0x60000
	v_readfirstlane_b32 s3, v155
	v_add_u32_e32 v0, 0xe000, v0
	global_load_lds_dwordx4 v[156:157], off
	v_lshl_add_u64 v[136:137], v[136:137], 0, s[4:5]
	s_mov_b32 m0, s3
	v_readfirstlane_b32 s3, v0
	global_load_lds_dwordx4 v[136:137], off
	v_lshl_add_u64 v[136:137], v[138:139], 0, s[4:5]
	s_mov_b32 m0, s3
	s_nop 0
	global_load_lds_dwordx4 v[136:137], off
	s_branch .LBB0_1421
